# GEMM phases: per-segment s_setprio toggling replaced by one static priority raise for waves 0-3
# speedup vs baseline: 1.0145x; 1.0040x over previous
_Z13mla_hgrn2_fwd6Params:
	s_load_dwordx2 s[64:65], s[0:1], 0x108
	s_load_dwordx4 s[56:59], s[0:1], 0x78
	s_add_u32 s10, s0, 0x108
	s_addc_u32 s11, s1, 0
	v_mov_b32_e32 v1, 0
	s_waitcnt lgkmcnt(0)
	s_cmp_lt_u32 s2, s64
	s_cselect_b32 s3, 12, 18
	s_add_u32 s4, s10, s3
	s_addc_u32 s5, s11, 0
	global_load_ushort v2, v1, s[4:5]
	v_and_b32_e32 v184, 0x3ff, v0
	v_cmp_eq_u32_e64 s[78:79], 0, v184
	v_readfirstlane_b32 s99, v184
	s_cmp_gt_u32 s99, 0xff
	s_cbranch_scc1 .Lgp_entry
	s_setprio 1

.LBB0_420:
	s_setprio 0
	s_cmp_gt_u32 s99, 0xff
	s_cbranch_scc1 .Lgp_att
	s_setprio 1
